# super-phase 1/3 MFMA blocks (with their 4 pre-barrier MFMAs) at priority 2, on top of v57
# speedup vs baseline: 1.0067x; 1.0065x over previous
.LBB0_233:
	ds_read_b128 v[130:133], v213
	ds_read_b128 v[134:137], v214
	ds_read_b128 v[138:141], v215
	ds_read_b128 v[142:145], v216
	ds_read_b128 v[146:149], v217
	ds_read_b128 v[150:153], v218
	ds_read_b128 v[154:157], v219
	ds_read_b128 v[158:161], v220
	s_add_i32 s4, s33, 0xffffe080
	s_cmp_eq_u32 s58, 12
	s_cselect_b32 s61, s18, s4
	s_cselect_b32 s60, s19, s57
	s_add_i32 s59, s61, 0x80
	s_mov_b32 s4, s70
	s_mov_b32 m0, s38
	ds_read_b128 v[162:165], v221
	ds_read_b128 v[166:169], v221 offset:2048
	ds_read_b128 v[170:173], v222
	ds_read_b128 v[174:177], v222 offset:2048
	ds_read_b128 v[178:181], v221 offset:4096
	ds_read_b128 v[182:185], v221 offset:6144
	ds_read_b128 v[186:189], v222 offset:4096
	ds_read_b128 v[190:193], v222 offset:6144
	buffer_load_dwordx4 v207, s[4:7], s33 offen lds
	s_mov_b32 m0, s41
	s_nop 0
	buffer_load_dwordx4 v209, s[4:7], s33 offen lds
	s_waitcnt vmcnt(8)
	s_waitcnt lgkmcnt(0)
	s_setprio 2
	v_mfma_f32_16x16x32_bf16 v[114:117], v[130:133], v[162:165], v[114:117]
	v_mfma_f32_16x16x32_bf16 v[110:113], v[138:141], v[162:165], v[110:113]
	v_mfma_f32_16x16x32_bf16 v[106:109], v[130:133], v[166:169], v[106:109]
	v_mfma_f32_16x16x32_bf16 v[102:105], v[138:141], v[166:169], v[102:105]
	s_barrier
	v_mfma_f32_16x16x32_bf16 v[98:101], v[130:133], v[178:181], v[98:101]
	v_mfma_f32_16x16x32_bf16 v[94:97], v[138:141], v[178:181], v[94:97]
	v_mfma_f32_16x16x32_bf16 v[90:93], v[130:133], v[182:185], v[90:93]
	v_mfma_f32_16x16x32_bf16 v[86:89], v[138:141], v[182:185], v[86:89]
	v_mfma_f32_16x16x32_bf16 v[114:117], v[134:137], v[170:173], v[114:117]
	v_mfma_f32_16x16x32_bf16 v[110:113], v[142:145], v[170:173], v[110:113]
	v_mfma_f32_16x16x32_bf16 v[106:109], v[134:137], v[174:177], v[106:109]
	v_mfma_f32_16x16x32_bf16 v[102:105], v[142:145], v[174:177], v[102:105]
	v_mfma_f32_16x16x32_bf16 v[98:101], v[134:137], v[186:189], v[98:101]
	v_mfma_f32_16x16x32_bf16 v[94:97], v[142:145], v[186:189], v[94:97]
	v_mfma_f32_16x16x32_bf16 v[90:93], v[134:137], v[190:193], v[90:93]
	v_mfma_f32_16x16x32_bf16 v[86:89], v[142:145], v[190:193], v[86:89]
	v_mfma_f32_16x16x32_bf16 v[82:85], v[146:149], v[162:165], v[82:85]
	v_mfma_f32_16x16x32_bf16 v[74:77], v[154:157], v[162:165], v[74:77]
	v_mfma_f32_16x16x32_bf16 v[70:73], v[146:149], v[166:169], v[70:73]
	v_mfma_f32_16x16x32_bf16 v[66:69], v[154:157], v[166:169], v[66:69]
	v_mfma_f32_16x16x32_bf16 v[62:65], v[146:149], v[178:181], v[62:65]
	v_mfma_f32_16x16x32_bf16 v[58:61], v[154:157], v[178:181], v[58:61]
	v_mfma_f32_16x16x32_bf16 v[54:57], v[146:149], v[182:185], v[54:57]
	v_mfma_f32_16x16x32_bf16 v[50:53], v[154:157], v[182:185], v[50:53]
	v_mfma_f32_16x16x32_bf16 v[82:85], v[150:153], v[170:173], v[82:85]
	v_mfma_f32_16x16x32_bf16 v[74:77], v[158:161], v[170:173], v[74:77]
	v_mfma_f32_16x16x32_bf16 v[70:73], v[150:153], v[174:177], v[70:73]
	v_mfma_f32_16x16x32_bf16 v[66:69], v[158:161], v[174:177], v[66:69]
	v_mfma_f32_16x16x32_bf16 v[62:65], v[150:153], v[186:189], v[62:65]
	v_mfma_f32_16x16x32_bf16 v[58:61], v[158:161], v[186:189], v[58:61]
	v_mfma_f32_16x16x32_bf16 v[54:57], v[150:153], v[190:193], v[54:57]
	v_mfma_f32_16x16x32_bf16 v[50:53], v[158:161], v[190:193], v[50:53]
	s_barrier
	s_setprio 0
	s_mov_b32 m0, s21
	ds_read_b128 v[162:165], v221 offset:16384
	ds_read_b128 v[166:169], v221 offset:18432
	ds_read_b128 v[170:173], v222 offset:16384
	ds_read_b128 v[174:177], v222 offset:18432
	ds_read_b128 v[178:181], v221 offset:20480
	ds_read_b128 v[182:185], v221 offset:22528
	ds_read_b128 v[186:189], v222 offset:20480
	ds_read_b128 v[190:193], v222 offset:22528
	buffer_load_dwordx4 v208, s[4:7], s60 offen lds
	s_mov_b32 m0, s22
	s_add_i32 s62, s60, 0x40000
	buffer_load_dwordx4 v210, s[4:7], s60 offen lds
	s_mov_b32 m0, s23
	s_nop 0
	buffer_load_dwordx4 v208, s[4:7], s62 offen lds
	s_mov_b32 m0, s24
	s_nop 0
	buffer_load_dwordx4 v210, s[4:7], s62 offen lds
	s_mov_b32 m0, s20
	s_nop 0
	buffer_load_dwordx4 v207, s[4:7], s61 offen lds
	s_mov_b32 m0, s25
	s_nop 0
	buffer_load_dwordx4 v209, s[4:7], s61 offen lds
	s_waitcnt vmcnt(8)
	s_waitcnt lgkmcnt(0)
	s_setprio 1
	s_barrier
	v_mfma_f32_16x16x32_bf16 v[78:81], v[130:133], v[162:165], v[78:81]
	v_mfma_f32_16x16x32_bf16 v[46:49], v[138:141], v[162:165], v[46:49]
	v_mfma_f32_16x16x32_bf16 v[42:45], v[130:133], v[166:169], v[42:45]
	v_mfma_f32_16x16x32_bf16 v[38:41], v[138:141], v[166:169], v[38:41]
	v_mfma_f32_16x16x32_bf16 v[34:37], v[130:133], v[178:181], v[34:37]
	v_mfma_f32_16x16x32_bf16 v[30:33], v[138:141], v[178:181], v[30:33]
	v_mfma_f32_16x16x32_bf16 v[26:29], v[130:133], v[182:185], v[26:29]
	v_mfma_f32_16x16x32_bf16 v[22:25], v[138:141], v[182:185], v[22:25]
	v_mfma_f32_16x16x32_bf16 v[78:81], v[134:137], v[170:173], v[78:81]
	v_mfma_f32_16x16x32_bf16 v[46:49], v[142:145], v[170:173], v[46:49]
	v_mfma_f32_16x16x32_bf16 v[42:45], v[134:137], v[174:177], v[42:45]
	v_mfma_f32_16x16x32_bf16 v[38:41], v[142:145], v[174:177], v[38:41]
	v_mfma_f32_16x16x32_bf16 v[34:37], v[134:137], v[186:189], v[34:37]
	v_mfma_f32_16x16x32_bf16 v[30:33], v[142:145], v[186:189], v[30:33]
	v_mfma_f32_16x16x32_bf16 v[26:29], v[134:137], v[190:193], v[26:29]
	v_mfma_f32_16x16x32_bf16 v[22:25], v[142:145], v[190:193], v[22:25]
	v_mfma_f32_16x16x32_bf16 v[18:21], v[146:149], v[162:165], v[18:21]
	v_mfma_f32_16x16x32_bf16 v[14:17], v[154:157], v[162:165], v[14:17]
	v_mfma_f32_16x16x32_bf16 v[10:13], v[146:149], v[166:169], v[10:13]
	v_mfma_f32_16x16x32_bf16 v[6:9], v[154:157], v[166:169], v[6:9]
	v_mfma_f32_16x16x32_bf16 v[2:5], v[146:149], v[178:181], v[2:5]
	v_mfma_f32_16x16x32_bf16 v[126:129], v[154:157], v[178:181], v[126:129]
	v_mfma_f32_16x16x32_bf16 v[122:125], v[146:149], v[182:185], v[122:125]
	v_mfma_f32_16x16x32_bf16 v[118:121], v[154:157], v[182:185], v[118:121]
	v_mfma_f32_16x16x32_bf16 v[18:21], v[150:153], v[170:173], v[18:21]
	v_mfma_f32_16x16x32_bf16 v[14:17], v[158:161], v[170:173], v[14:17]
	v_mfma_f32_16x16x32_bf16 v[10:13], v[150:153], v[174:177], v[10:13]
	v_mfma_f32_16x16x32_bf16 v[6:9], v[158:161], v[174:177], v[6:9]
	v_mfma_f32_16x16x32_bf16 v[2:5], v[150:153], v[186:189], v[2:5]
	v_mfma_f32_16x16x32_bf16 v[126:129], v[158:161], v[186:189], v[126:129]
	v_mfma_f32_16x16x32_bf16 v[122:125], v[150:153], v[190:193], v[122:125]
	v_mfma_f32_16x16x32_bf16 v[118:121], v[158:161], v[190:193], v[118:121]
	s_barrier
	s_setprio 0
	ds_read_b128 v[130:133], v194
	ds_read_b128 v[134:137], v224
	ds_read_b128 v[138:141], v225
	ds_read_b128 v[142:145], v228
	ds_read_b128 v[146:149], v229
	ds_read_b128 v[150:153], v230
	ds_read_b128 v[154:157], v231
	ds_read_b128 v[158:161], v233
	s_addk_i32 s61, 0x2000
	s_mov_b32 m0, s26
	ds_read_b128 v[162:165], v221 offset:32768
	ds_read_b128 v[166:169], v221 offset:34816
	ds_read_b128 v[170:173], v222 offset:32768
	ds_read_b128 v[174:177], v222 offset:34816
	ds_read_b128 v[178:181], v221 offset:36864
	ds_read_b128 v[182:185], v221 offset:38912
	ds_read_b128 v[186:189], v222 offset:36864
	ds_read_b128 v[190:193], v222 offset:38912
	buffer_load_dwordx4 v207, s[4:7], s61 offen lds
	s_mov_b32 m0, s27
	s_nop 0
	buffer_load_dwordx4 v209, s[4:7], s61 offen lds
	s_waitcnt vmcnt(8)
	s_waitcnt lgkmcnt(0)
	s_setprio 2
	v_mfma_f32_16x16x32_bf16 v[114:117], v[130:133], v[162:165], v[114:117]
	v_mfma_f32_16x16x32_bf16 v[110:113], v[138:141], v[162:165], v[110:113]
	v_mfma_f32_16x16x32_bf16 v[106:109], v[130:133], v[166:169], v[106:109]
	v_mfma_f32_16x16x32_bf16 v[102:105], v[138:141], v[166:169], v[102:105]
	s_barrier
	v_mfma_f32_16x16x32_bf16 v[98:101], v[130:133], v[178:181], v[98:101]
	v_mfma_f32_16x16x32_bf16 v[94:97], v[138:141], v[178:181], v[94:97]
	v_mfma_f32_16x16x32_bf16 v[90:93], v[130:133], v[182:185], v[90:93]
	v_mfma_f32_16x16x32_bf16 v[86:89], v[138:141], v[182:185], v[86:89]
	v_mfma_f32_16x16x32_bf16 v[114:117], v[134:137], v[170:173], v[114:117]
	v_mfma_f32_16x16x32_bf16 v[110:113], v[142:145], v[170:173], v[110:113]
	v_mfma_f32_16x16x32_bf16 v[106:109], v[134:137], v[174:177], v[106:109]
	v_mfma_f32_16x16x32_bf16 v[102:105], v[142:145], v[174:177], v[102:105]
	v_mfma_f32_16x16x32_bf16 v[98:101], v[134:137], v[186:189], v[98:101]
	v_mfma_f32_16x16x32_bf16 v[94:97], v[142:145], v[186:189], v[94:97]
	v_mfma_f32_16x16x32_bf16 v[90:93], v[134:137], v[190:193], v[90:93]
	v_mfma_f32_16x16x32_bf16 v[86:89], v[142:145], v[190:193], v[86:89]
	v_mfma_f32_16x16x32_bf16 v[82:85], v[146:149], v[162:165], v[82:85]
	v_mfma_f32_16x16x32_bf16 v[74:77], v[154:157], v[162:165], v[74:77]
	v_mfma_f32_16x16x32_bf16 v[70:73], v[146:149], v[166:169], v[70:73]
	v_mfma_f32_16x16x32_bf16 v[66:69], v[154:157], v[166:169], v[66:69]
	v_mfma_f32_16x16x32_bf16 v[62:65], v[146:149], v[178:181], v[62:65]
	v_mfma_f32_16x16x32_bf16 v[58:61], v[154:157], v[178:181], v[58:61]
	v_mfma_f32_16x16x32_bf16 v[54:57], v[146:149], v[182:185], v[54:57]
	v_mfma_f32_16x16x32_bf16 v[50:53], v[154:157], v[182:185], v[50:53]
	v_mfma_f32_16x16x32_bf16 v[82:85], v[150:153], v[170:173], v[82:85]
	v_mfma_f32_16x16x32_bf16 v[74:77], v[158:161], v[170:173], v[74:77]
	v_mfma_f32_16x16x32_bf16 v[70:73], v[150:153], v[174:177], v[70:73]
	v_mfma_f32_16x16x32_bf16 v[66:69], v[158:161], v[174:177], v[66:69]
	v_mfma_f32_16x16x32_bf16 v[62:65], v[150:153], v[186:189], v[62:65]
	v_mfma_f32_16x16x32_bf16 v[58:61], v[158:161], v[186:189], v[58:61]
	v_mfma_f32_16x16x32_bf16 v[54:57], v[150:153], v[190:193], v[54:57]
	v_mfma_f32_16x16x32_bf16 v[50:53], v[158:161], v[190:193], v[50:53]
	s_barrier
	s_setprio 0
	s_mov_b32 m0, s29
	s_add_i32 s61, s60, 0x80
	ds_read_b128 v[162:165], v221 offset:49152
	ds_read_b128 v[166:169], v221 offset:51200
	ds_read_b128 v[170:173], v222 offset:49152
	ds_read_b128 v[174:177], v222 offset:51200
	ds_read_b128 v[178:181], v221 offset:53248
	ds_read_b128 v[182:185], v221 offset:55296
	ds_read_b128 v[186:189], v222 offset:53248
	ds_read_b128 v[190:193], v222 offset:55296
	buffer_load_dwordx4 v208, s[4:7], s61 offen lds
	s_mov_b32 m0, s30
	s_add_i32 s60, s60, 0x40080
	buffer_load_dwordx4 v210, s[4:7], s61 offen lds
	s_mov_b32 m0, s35
	s_nop 0
	buffer_load_dwordx4 v208, s[4:7], s60 offen lds
	s_mov_b32 m0, s36
	s_nop 0
	buffer_load_dwordx4 v210, s[4:7], s60 offen lds
	s_mov_b32 m0, s31
	s_nop 0
	buffer_load_dwordx4 v207, s[4:7], s59 offen lds
	s_mov_b32 m0, s34
	s_nop 0
	buffer_load_dwordx4 v209, s[4:7], s59 offen lds
	s_waitcnt vmcnt(8)
	s_waitcnt lgkmcnt(0)
	s_setprio 1
	s_barrier
	v_mfma_f32_16x16x32_bf16 v[78:81], v[130:133], v[162:165], v[78:81]
	v_mfma_f32_16x16x32_bf16 v[46:49], v[138:141], v[162:165], v[46:49]
	v_mfma_f32_16x16x32_bf16 v[42:45], v[130:133], v[166:169], v[42:45]
	v_mfma_f32_16x16x32_bf16 v[38:41], v[138:141], v[166:169], v[38:41]
	v_mfma_f32_16x16x32_bf16 v[34:37], v[130:133], v[178:181], v[34:37]
	v_mfma_f32_16x16x32_bf16 v[30:33], v[138:141], v[178:181], v[30:33]
	v_mfma_f32_16x16x32_bf16 v[26:29], v[130:133], v[182:185], v[26:29]
	v_mfma_f32_16x16x32_bf16 v[22:25], v[138:141], v[182:185], v[22:25]
	v_mfma_f32_16x16x32_bf16 v[78:81], v[134:137], v[170:173], v[78:81]
	v_mfma_f32_16x16x32_bf16 v[46:49], v[142:145], v[170:173], v[46:49]
	v_mfma_f32_16x16x32_bf16 v[42:45], v[134:137], v[174:177], v[42:45]
	v_mfma_f32_16x16x32_bf16 v[38:41], v[142:145], v[174:177], v[38:41]
	v_mfma_f32_16x16x32_bf16 v[34:37], v[134:137], v[186:189], v[34:37]
	v_mfma_f32_16x16x32_bf16 v[30:33], v[142:145], v[186:189], v[30:33]
	v_mfma_f32_16x16x32_bf16 v[26:29], v[134:137], v[190:193], v[26:29]
	v_mfma_f32_16x16x32_bf16 v[22:25], v[142:145], v[190:193], v[22:25]
	v_mfma_f32_16x16x32_bf16 v[18:21], v[146:149], v[162:165], v[18:21]
	v_mfma_f32_16x16x32_bf16 v[14:17], v[154:157], v[162:165], v[14:17]
	v_mfma_f32_16x16x32_bf16 v[10:13], v[146:149], v[166:169], v[10:13]
	v_mfma_f32_16x16x32_bf16 v[6:9], v[154:157], v[166:169], v[6:9]
	v_mfma_f32_16x16x32_bf16 v[2:5], v[146:149], v[178:181], v[2:5]
	v_mfma_f32_16x16x32_bf16 v[126:129], v[154:157], v[178:181], v[126:129]
	v_mfma_f32_16x16x32_bf16 v[122:125], v[146:149], v[182:185], v[122:125]
	v_mfma_f32_16x16x32_bf16 v[118:121], v[154:157], v[182:185], v[118:121]
	v_mfma_f32_16x16x32_bf16 v[18:21], v[150:153], v[170:173], v[18:21]
	v_mfma_f32_16x16x32_bf16 v[14:17], v[158:161], v[170:173], v[14:17]
	v_mfma_f32_16x16x32_bf16 v[10:13], v[150:153], v[174:177], v[10:13]
	v_mfma_f32_16x16x32_bf16 v[6:9], v[158:161], v[174:177], v[6:9]
	v_mfma_f32_16x16x32_bf16 v[2:5], v[150:153], v[186:189], v[2:5]
	v_mfma_f32_16x16x32_bf16 v[126:129], v[158:161], v[186:189], v[126:129]
	v_mfma_f32_16x16x32_bf16 v[122:125], v[150:153], v[190:193], v[122:125]
	v_mfma_f32_16x16x32_bf16 v[118:121], v[158:161], v[190:193], v[118:121]
	s_barrier
	s_setprio 0
	s_add_i32 s58, s58, 2
	s_addk_i32 s33, 0x100
	s_addk_i32 s57, 0x100
	s_cmp_gt_u32 s58, 13
	s_cbranch_scc0 .LBB0_233
	s_and_b64 vcc, exec, s[16:17]
	s_cbranch_vccz .LBB0_236
	s_barrier

.LBB0_546:
	ds_read_b128 v[130:133], v211
	ds_read_b128 v[134:137], v212
	ds_read_b128 v[138:141], v213
	ds_read_b128 v[142:145], v214
	ds_read_b128 v[146:149], v215
	ds_read_b128 v[150:153], v216
	ds_read_b128 v[154:157], v217
	ds_read_b128 v[158:161], v218
	s_add_i32 s4, s62, 0x80
	s_cmp_eq_u32 s63, s78
	s_cselect_b32 s84, s64, s4
	s_cselect_b32 s82, s33, s59
	s_cselect_b32 s81, s65, s61
	s_cselect_b32 s80, s56, s60
	s_add_i32 s79, s84, 0x80
	s_add_i32 s83, s60, s62
	s_mov_b32 s4, s70
	s_mov_b32 m0, s43
	ds_read_b128 v[162:165], v219
	ds_read_b128 v[166:169], v219 offset:2048
	ds_read_b128 v[170:173], v220
	ds_read_b128 v[174:177], v220 offset:2048
	ds_read_b128 v[178:181], v219 offset:4096
	ds_read_b128 v[182:185], v219 offset:6144
	ds_read_b128 v[186:189], v220 offset:4096
	ds_read_b128 v[190:193], v220 offset:6144
	buffer_load_dwordx4 v194, s[4:7], s83 offen lds
	s_mov_b32 m0, s44
	s_nop 0
	buffer_load_dwordx4 v222, s[4:7], s83 offen lds
	s_waitcnt vmcnt(8)
	s_waitcnt lgkmcnt(0)
	s_setprio 2
	v_mfma_f32_16x16x32_bf16 v[126:129], v[130:133], v[162:165], v[126:129]
	v_mfma_f32_16x16x32_bf16 v[122:125], v[138:141], v[162:165], v[122:125]
	v_mfma_f32_16x16x32_bf16 v[118:121], v[130:133], v[166:169], v[118:121]
	v_mfma_f32_16x16x32_bf16 v[114:117], v[138:141], v[166:169], v[114:117]
	s_barrier
	v_mfma_f32_16x16x32_bf16 v[110:113], v[130:133], v[178:181], v[110:113]
	v_mfma_f32_16x16x32_bf16 v[106:109], v[138:141], v[178:181], v[106:109]
	v_mfma_f32_16x16x32_bf16 v[102:105], v[130:133], v[182:185], v[102:105]
	v_mfma_f32_16x16x32_bf16 v[98:101], v[138:141], v[182:185], v[98:101]
	v_mfma_f32_16x16x32_bf16 v[126:129], v[134:137], v[170:173], v[126:129]
	v_mfma_f32_16x16x32_bf16 v[122:125], v[142:145], v[170:173], v[122:125]
	v_mfma_f32_16x16x32_bf16 v[118:121], v[134:137], v[174:177], v[118:121]
	v_mfma_f32_16x16x32_bf16 v[114:117], v[142:145], v[174:177], v[114:117]
	v_mfma_f32_16x16x32_bf16 v[110:113], v[134:137], v[186:189], v[110:113]
	v_mfma_f32_16x16x32_bf16 v[106:109], v[142:145], v[186:189], v[106:109]
	v_mfma_f32_16x16x32_bf16 v[102:105], v[134:137], v[190:193], v[102:105]
	v_mfma_f32_16x16x32_bf16 v[98:101], v[142:145], v[190:193], v[98:101]
	v_mfma_f32_16x16x32_bf16 v[94:97], v[146:149], v[162:165], v[94:97]
	v_mfma_f32_16x16x32_bf16 v[90:93], v[154:157], v[162:165], v[90:93]
	v_mfma_f32_16x16x32_bf16 v[86:89], v[146:149], v[166:169], v[86:89]
	v_mfma_f32_16x16x32_bf16 v[82:85], v[154:157], v[166:169], v[82:85]
	v_mfma_f32_16x16x32_bf16 v[78:81], v[146:149], v[178:181], v[78:81]
	v_mfma_f32_16x16x32_bf16 v[74:77], v[154:157], v[178:181], v[74:77]
	v_mfma_f32_16x16x32_bf16 v[70:73], v[146:149], v[182:185], v[70:73]
	v_mfma_f32_16x16x32_bf16 v[66:69], v[154:157], v[182:185], v[66:69]
	v_mfma_f32_16x16x32_bf16 v[94:97], v[150:153], v[170:173], v[94:97]
	v_mfma_f32_16x16x32_bf16 v[90:93], v[158:161], v[170:173], v[90:93]
	v_mfma_f32_16x16x32_bf16 v[86:89], v[150:153], v[174:177], v[86:89]
	v_mfma_f32_16x16x32_bf16 v[82:85], v[158:161], v[174:177], v[82:85]
	v_mfma_f32_16x16x32_bf16 v[78:81], v[150:153], v[186:189], v[78:81]
	v_mfma_f32_16x16x32_bf16 v[74:77], v[158:161], v[186:189], v[74:77]
	v_mfma_f32_16x16x32_bf16 v[70:73], v[150:153], v[190:193], v[70:73]
	v_mfma_f32_16x16x32_bf16 v[66:69], v[158:161], v[190:193], v[66:69]
	s_barrier
	s_setprio 0
	s_cmp_eq_u32 s82, 0
	s_cselect_b64 s[82:83], -1, 0
	v_cndmask_b32_e64 v233, v200, 0, s[82:83]
	s_mov_b32 m0, s25
	v_sub_u32_e32 v233, v201, v233
	v_cndmask_b32_e64 v234, v203, 0, s[82:83]
	ds_read_b128 v[162:165], v219 offset:16384
	ds_read_b128 v[166:169], v219 offset:18432
	ds_read_b128 v[170:173], v220 offset:16384
	ds_read_b128 v[174:177], v220 offset:18432
	ds_read_b128 v[178:181], v219 offset:20480
	ds_read_b128 v[182:185], v219 offset:22528
	ds_read_b128 v[186:189], v220 offset:20480
	ds_read_b128 v[190:193], v220 offset:22528
	buffer_load_dwordx4 v233, s[4:7], s81 offen lds
	v_sub_u32_e32 v234, v204, v234
	s_mov_b32 m0, s26
	s_add_i32 s85, s81, s80
	buffer_load_dwordx4 v234, s[4:7], s81 offen lds
	s_mov_b32 m0, s27
	v_cndmask_b32_e64 v235, v205, 0, s[82:83]
	buffer_load_dwordx4 v233, s[4:7], s85 offen lds
	s_mov_b32 m0, s28
	v_sub_u32_e32 v235, v1, v235
	buffer_load_dwordx4 v234, s[4:7], s85 offen lds
	s_mov_b32 m0, s24
	v_cndmask_b32_e64 v236, v206, 0, s[82:83]
	buffer_load_dwordx4 v235, s[4:7], s84 offen lds
	v_sub_u32_e32 v236, v202, v236
	s_mov_b32 m0, s29
	s_nop 0
	buffer_load_dwordx4 v236, s[4:7], s84 offen lds
	s_waitcnt vmcnt(8)
	s_waitcnt lgkmcnt(0)
	s_setprio 1
	s_barrier
	v_mfma_f32_16x16x32_bf16 v[62:65], v[130:133], v[162:165], v[62:65]
	v_mfma_f32_16x16x32_bf16 v[58:61], v[138:141], v[162:165], v[58:61]
	v_mfma_f32_16x16x32_bf16 v[54:57], v[130:133], v[166:169], v[54:57]
	v_mfma_f32_16x16x32_bf16 v[50:53], v[138:141], v[166:169], v[50:53]
	v_mfma_f32_16x16x32_bf16 v[46:49], v[130:133], v[178:181], v[46:49]
	v_mfma_f32_16x16x32_bf16 v[42:45], v[138:141], v[178:181], v[42:45]
	v_mfma_f32_16x16x32_bf16 v[38:41], v[130:133], v[182:185], v[38:41]
	v_mfma_f32_16x16x32_bf16 v[34:37], v[138:141], v[182:185], v[34:37]
	v_mfma_f32_16x16x32_bf16 v[62:65], v[134:137], v[170:173], v[62:65]
	v_mfma_f32_16x16x32_bf16 v[58:61], v[142:145], v[170:173], v[58:61]
	v_mfma_f32_16x16x32_bf16 v[54:57], v[134:137], v[174:177], v[54:57]
	v_mfma_f32_16x16x32_bf16 v[50:53], v[142:145], v[174:177], v[50:53]
	v_mfma_f32_16x16x32_bf16 v[46:49], v[134:137], v[186:189], v[46:49]
	v_mfma_f32_16x16x32_bf16 v[42:45], v[142:145], v[186:189], v[42:45]
	v_mfma_f32_16x16x32_bf16 v[38:41], v[134:137], v[190:193], v[38:41]
	v_mfma_f32_16x16x32_bf16 v[34:37], v[142:145], v[190:193], v[34:37]
	v_mfma_f32_16x16x32_bf16 v[30:33], v[146:149], v[162:165], v[30:33]
	v_mfma_f32_16x16x32_bf16 v[26:29], v[154:157], v[162:165], v[26:29]
	v_mfma_f32_16x16x32_bf16 v[22:25], v[146:149], v[166:169], v[22:25]
	v_mfma_f32_16x16x32_bf16 v[18:21], v[154:157], v[166:169], v[18:21]
	v_mfma_f32_16x16x32_bf16 v[14:17], v[146:149], v[178:181], v[14:17]
	v_mfma_f32_16x16x32_bf16 v[10:13], v[154:157], v[178:181], v[10:13]
	v_mfma_f32_16x16x32_bf16 v[6:9], v[146:149], v[182:185], v[6:9]
	v_mfma_f32_16x16x32_bf16 v[2:5], v[154:157], v[182:185], v[2:5]
	v_mfma_f32_16x16x32_bf16 v[30:33], v[150:153], v[170:173], v[30:33]
	v_mfma_f32_16x16x32_bf16 v[26:29], v[158:161], v[170:173], v[26:29]
	v_mfma_f32_16x16x32_bf16 v[22:25], v[150:153], v[174:177], v[22:25]
	v_mfma_f32_16x16x32_bf16 v[18:21], v[158:161], v[174:177], v[18:21]
	v_mfma_f32_16x16x32_bf16 v[14:17], v[150:153], v[186:189], v[14:17]
	v_mfma_f32_16x16x32_bf16 v[10:13], v[158:161], v[186:189], v[10:13]
	v_mfma_f32_16x16x32_bf16 v[6:9], v[150:153], v[190:193], v[6:9]
	v_mfma_f32_16x16x32_bf16 v[2:5], v[158:161], v[190:193], v[2:5]
	s_barrier
	s_setprio 0
	ds_read_b128 v[130:133], v223
	ds_read_b128 v[134:137], v224
	ds_read_b128 v[138:141], v225
	ds_read_b128 v[142:145], v227
	ds_read_b128 v[146:149], v228
	ds_read_b128 v[150:153], v229
	ds_read_b128 v[154:157], v230
	ds_read_b128 v[158:161], v231
	s_add_i32 s84, s84, s80
	s_mov_b32 m0, s30
	ds_read_b128 v[162:165], v219 offset:32768
	ds_read_b128 v[166:169], v219 offset:34816
	ds_read_b128 v[170:173], v220 offset:32768
	ds_read_b128 v[174:177], v220 offset:34816
	ds_read_b128 v[178:181], v219 offset:36864
	ds_read_b128 v[182:185], v219 offset:38912
	ds_read_b128 v[186:189], v220 offset:36864
	ds_read_b128 v[190:193], v220 offset:38912
	buffer_load_dwordx4 v235, s[4:7], s84 offen lds
	s_mov_b32 m0, s31
	s_nop 0
	buffer_load_dwordx4 v236, s[4:7], s84 offen lds
	s_waitcnt vmcnt(8)
	s_waitcnt lgkmcnt(0)
	s_setprio 2
	v_mfma_f32_16x16x32_bf16 v[126:129], v[130:133], v[162:165], v[126:129]
	v_mfma_f32_16x16x32_bf16 v[122:125], v[138:141], v[162:165], v[122:125]
	v_mfma_f32_16x16x32_bf16 v[118:121], v[130:133], v[166:169], v[118:121]
	v_mfma_f32_16x16x32_bf16 v[114:117], v[138:141], v[166:169], v[114:117]
	s_barrier
	v_mfma_f32_16x16x32_bf16 v[110:113], v[130:133], v[178:181], v[110:113]
	v_mfma_f32_16x16x32_bf16 v[106:109], v[138:141], v[178:181], v[106:109]
	v_mfma_f32_16x16x32_bf16 v[102:105], v[130:133], v[182:185], v[102:105]
	v_mfma_f32_16x16x32_bf16 v[98:101], v[138:141], v[182:185], v[98:101]
	v_mfma_f32_16x16x32_bf16 v[126:129], v[134:137], v[170:173], v[126:129]
	v_mfma_f32_16x16x32_bf16 v[122:125], v[142:145], v[170:173], v[122:125]
	v_mfma_f32_16x16x32_bf16 v[118:121], v[134:137], v[174:177], v[118:121]
	v_mfma_f32_16x16x32_bf16 v[114:117], v[142:145], v[174:177], v[114:117]
	v_mfma_f32_16x16x32_bf16 v[110:113], v[134:137], v[186:189], v[110:113]
	v_mfma_f32_16x16x32_bf16 v[106:109], v[142:145], v[186:189], v[106:109]
	v_mfma_f32_16x16x32_bf16 v[102:105], v[134:137], v[190:193], v[102:105]
	v_mfma_f32_16x16x32_bf16 v[98:101], v[142:145], v[190:193], v[98:101]
	v_mfma_f32_16x16x32_bf16 v[94:97], v[146:149], v[162:165], v[94:97]
	v_mfma_f32_16x16x32_bf16 v[90:93], v[154:157], v[162:165], v[90:93]
	v_mfma_f32_16x16x32_bf16 v[86:89], v[146:149], v[166:169], v[86:89]
	v_mfma_f32_16x16x32_bf16 v[82:85], v[154:157], v[166:169], v[82:85]
	v_mfma_f32_16x16x32_bf16 v[78:81], v[146:149], v[178:181], v[78:81]
	v_mfma_f32_16x16x32_bf16 v[74:77], v[154:157], v[178:181], v[74:77]
	v_mfma_f32_16x16x32_bf16 v[70:73], v[146:149], v[182:185], v[70:73]
	v_mfma_f32_16x16x32_bf16 v[66:69], v[154:157], v[182:185], v[66:69]
	v_mfma_f32_16x16x32_bf16 v[94:97], v[150:153], v[170:173], v[94:97]
	v_mfma_f32_16x16x32_bf16 v[90:93], v[158:161], v[170:173], v[90:93]
	v_mfma_f32_16x16x32_bf16 v[86:89], v[150:153], v[174:177], v[86:89]
	v_mfma_f32_16x16x32_bf16 v[82:85], v[158:161], v[174:177], v[82:85]
	v_mfma_f32_16x16x32_bf16 v[78:81], v[150:153], v[186:189], v[78:81]
	v_mfma_f32_16x16x32_bf16 v[74:77], v[158:161], v[186:189], v[74:77]
	v_mfma_f32_16x16x32_bf16 v[70:73], v[150:153], v[190:193], v[70:73]
	v_mfma_f32_16x16x32_bf16 v[66:69], v[158:161], v[190:193], v[66:69]
	s_barrier
	s_setprio 0
	s_mov_b32 m0, s36
	s_addk_i32 s81, 0x80
	ds_read_b128 v[162:165], v219 offset:49152
	ds_read_b128 v[166:169], v219 offset:51200
	ds_read_b128 v[170:173], v220 offset:49152
	ds_read_b128 v[174:177], v220 offset:51200
	ds_read_b128 v[178:181], v219 offset:53248
	ds_read_b128 v[182:185], v219 offset:55296
	ds_read_b128 v[186:189], v220 offset:53248
	ds_read_b128 v[190:193], v220 offset:55296
	buffer_load_dwordx4 v233, s[4:7], s81 offen lds
	s_mov_b32 m0, s37
	s_nop 0
	buffer_load_dwordx4 v234, s[4:7], s81 offen lds
	s_add_i32 s81, s81, s80
	s_mov_b32 m0, s40
	s_nop 0
	buffer_load_dwordx4 v233, s[4:7], s81 offen lds
	s_mov_b32 m0, s41
	s_nop 0
	buffer_load_dwordx4 v234, s[4:7], s81 offen lds
	s_mov_b32 m0, s38
	s_nop 0
	buffer_load_dwordx4 v235, s[4:7], s79 offen lds
	s_mov_b32 m0, s39
	s_nop 0
	buffer_load_dwordx4 v236, s[4:7], s79 offen lds
	s_waitcnt vmcnt(8)
	s_waitcnt lgkmcnt(0)
	s_setprio 1
	s_barrier
	v_mfma_f32_16x16x32_bf16 v[62:65], v[130:133], v[162:165], v[62:65]
	v_mfma_f32_16x16x32_bf16 v[58:61], v[138:141], v[162:165], v[58:61]
	v_mfma_f32_16x16x32_bf16 v[54:57], v[130:133], v[166:169], v[54:57]
	v_mfma_f32_16x16x32_bf16 v[50:53], v[138:141], v[166:169], v[50:53]
	v_mfma_f32_16x16x32_bf16 v[46:49], v[130:133], v[178:181], v[46:49]
	v_mfma_f32_16x16x32_bf16 v[42:45], v[138:141], v[178:181], v[42:45]
	v_mfma_f32_16x16x32_bf16 v[38:41], v[130:133], v[182:185], v[38:41]
	v_mfma_f32_16x16x32_bf16 v[34:37], v[138:141], v[182:185], v[34:37]
	v_mfma_f32_16x16x32_bf16 v[62:65], v[134:137], v[170:173], v[62:65]
	v_mfma_f32_16x16x32_bf16 v[58:61], v[142:145], v[170:173], v[58:61]
	v_mfma_f32_16x16x32_bf16 v[54:57], v[134:137], v[174:177], v[54:57]
	v_mfma_f32_16x16x32_bf16 v[50:53], v[142:145], v[174:177], v[50:53]
	v_mfma_f32_16x16x32_bf16 v[46:49], v[134:137], v[186:189], v[46:49]
	v_mfma_f32_16x16x32_bf16 v[42:45], v[142:145], v[186:189], v[42:45]
	v_mfma_f32_16x16x32_bf16 v[38:41], v[134:137], v[190:193], v[38:41]
	v_mfma_f32_16x16x32_bf16 v[34:37], v[142:145], v[190:193], v[34:37]
	v_mfma_f32_16x16x32_bf16 v[30:33], v[146:149], v[162:165], v[30:33]
	v_mfma_f32_16x16x32_bf16 v[26:29], v[154:157], v[162:165], v[26:29]
	v_mfma_f32_16x16x32_bf16 v[22:25], v[146:149], v[166:169], v[22:25]
	v_mfma_f32_16x16x32_bf16 v[18:21], v[154:157], v[166:169], v[18:21]
	v_mfma_f32_16x16x32_bf16 v[14:17], v[146:149], v[178:181], v[14:17]
	v_mfma_f32_16x16x32_bf16 v[10:13], v[154:157], v[178:181], v[10:13]
	v_mfma_f32_16x16x32_bf16 v[6:9], v[146:149], v[182:185], v[6:9]
	v_mfma_f32_16x16x32_bf16 v[2:5], v[154:157], v[182:185], v[2:5]
	v_mfma_f32_16x16x32_bf16 v[30:33], v[150:153], v[170:173], v[30:33]
	v_mfma_f32_16x16x32_bf16 v[26:29], v[158:161], v[170:173], v[26:29]
	v_mfma_f32_16x16x32_bf16 v[22:25], v[150:153], v[174:177], v[22:25]
	v_mfma_f32_16x16x32_bf16 v[18:21], v[158:161], v[174:177], v[18:21]
	v_mfma_f32_16x16x32_bf16 v[14:17], v[150:153], v[186:189], v[14:17]
	v_mfma_f32_16x16x32_bf16 v[10:13], v[158:161], v[186:189], v[10:13]
	v_mfma_f32_16x16x32_bf16 v[6:9], v[150:153], v[190:193], v[6:9]
	v_mfma_f32_16x16x32_bf16 v[2:5], v[158:161], v[190:193], v[2:5]
	s_barrier
	s_setprio 0
	s_add_i32 s4, s78, 2
	s_addk_i32 s62, 0x100
	s_addk_i32 s61, 0x100
	s_cmp_ge_u32 s78, s63
	s_mov_b32 s78, s4
	s_cbranch_scc0 .LBB0_546
	s_and_b64 vcc, exec, s[12:13]
	s_cbranch_vccz .LBB0_549
	s_barrier

.LBB0_841:
	ds_read_b128 v[130:133], v240
	ds_read_b128 v[134:137], v241
	ds_read_b128 v[138:141], v242
	ds_read_b128 v[142:145], v243
	ds_read_b128 v[146:149], v244
	ds_read_b128 v[150:153], v245
	ds_read_b128 v[154:157], v246
	ds_read_b128 v[158:161], v247
	s_add_i32 s8, s42, s5
	s_add_i32 s19, s34, s5
	s_add_i32 s18, s8, 0x800
	s_addk_i32 s19, 0x800
	s_cmp_eq_u32 s5, 0
	s_cselect_b32 s20, s0, s18
	s_cselect_b32 s19, s1, s19
	s_add_i32 s18, s20, 0x80
	s_add_i32 s21, s8, 0x40780
	s_mov_b32 s8, s70
	s_mov_b32 m0, s52
	ds_read_b128 v[162:165], v248
	ds_read_b128 v[166:169], v248 offset:2048
	ds_read_b128 v[170:173], v249
	ds_read_b128 v[174:177], v249 offset:2048
	ds_read_b128 v[178:181], v248 offset:4096
	ds_read_b128 v[182:185], v248 offset:6144
	ds_read_b128 v[186:189], v249 offset:4096
	ds_read_b128 v[190:193], v249 offset:6144
	buffer_load_dwordx4 v1, s[8:11], s21 offen lds
	s_mov_b32 m0, s53
	s_nop 0
	buffer_load_dwordx4 v234, s[8:11], s21 offen lds
	s_waitcnt vmcnt(8)
	s_waitcnt lgkmcnt(0)
	s_setprio 2
	v_mfma_f32_16x16x32_bf16 v[74:77], v[130:133], v[162:165], v[74:77]
	v_mfma_f32_16x16x32_bf16 v[70:73], v[138:141], v[162:165], v[70:73]
	v_mfma_f32_16x16x32_bf16 v[66:69], v[130:133], v[166:169], v[66:69]
	v_mfma_f32_16x16x32_bf16 v[82:85], v[138:141], v[166:169], v[82:85]
	s_barrier
	v_mfma_f32_16x16x32_bf16 v[78:81], v[130:133], v[178:181], v[78:81]
	v_mfma_f32_16x16x32_bf16 v[90:93], v[138:141], v[178:181], v[90:93]
	v_mfma_f32_16x16x32_bf16 v[86:89], v[130:133], v[182:185], v[86:89]
	v_mfma_f32_16x16x32_bf16 v[102:105], v[138:141], v[182:185], v[102:105]
	v_mfma_f32_16x16x32_bf16 v[74:77], v[134:137], v[170:173], v[74:77]
	v_mfma_f32_16x16x32_bf16 v[70:73], v[142:145], v[170:173], v[70:73]
	v_mfma_f32_16x16x32_bf16 v[66:69], v[134:137], v[174:177], v[66:69]
	v_mfma_f32_16x16x32_bf16 v[82:85], v[142:145], v[174:177], v[82:85]
	v_mfma_f32_16x16x32_bf16 v[78:81], v[134:137], v[186:189], v[78:81]
	v_mfma_f32_16x16x32_bf16 v[90:93], v[142:145], v[186:189], v[90:93]
	v_mfma_f32_16x16x32_bf16 v[86:89], v[134:137], v[190:193], v[86:89]
	v_mfma_f32_16x16x32_bf16 v[102:105], v[142:145], v[190:193], v[102:105]
	v_mfma_f32_16x16x32_bf16 v[98:101], v[146:149], v[162:165], v[98:101]
	v_mfma_f32_16x16x32_bf16 v[94:97], v[154:157], v[162:165], v[94:97]
	v_mfma_f32_16x16x32_bf16 v[106:109], v[146:149], v[166:169], v[106:109]
	v_mfma_f32_16x16x32_bf16 v[110:113], v[154:157], v[166:169], v[110:113]
	v_mfma_f32_16x16x32_bf16 v[114:117], v[146:149], v[178:181], v[114:117]
	v_mfma_f32_16x16x32_bf16 v[118:121], v[154:157], v[178:181], v[118:121]
	v_mfma_f32_16x16x32_bf16 v[122:125], v[146:149], v[182:185], v[122:125]
	v_mfma_f32_16x16x32_bf16 v[126:129], v[154:157], v[182:185], v[126:129]
	v_mfma_f32_16x16x32_bf16 v[98:101], v[150:153], v[170:173], v[98:101]
	v_mfma_f32_16x16x32_bf16 v[94:97], v[158:161], v[170:173], v[94:97]
	v_mfma_f32_16x16x32_bf16 v[106:109], v[150:153], v[174:177], v[106:109]
	v_mfma_f32_16x16x32_bf16 v[110:113], v[158:161], v[174:177], v[110:113]
	v_mfma_f32_16x16x32_bf16 v[114:117], v[150:153], v[186:189], v[114:117]
	v_mfma_f32_16x16x32_bf16 v[118:121], v[158:161], v[186:189], v[118:121]
	v_mfma_f32_16x16x32_bf16 v[122:125], v[150:153], v[190:193], v[122:125]
	v_mfma_f32_16x16x32_bf16 v[126:129], v[158:161], v[190:193], v[126:129]
	s_barrier
	s_setprio 0
	s_mov_b32 m0, s29
	ds_read_b128 v[162:165], v248 offset:16384
	ds_read_b128 v[166:169], v248 offset:18432
	ds_read_b128 v[170:173], v249 offset:16384
	ds_read_b128 v[174:177], v249 offset:18432
	ds_read_b128 v[178:181], v248 offset:20480
	ds_read_b128 v[182:185], v248 offset:22528
	ds_read_b128 v[186:189], v249 offset:20480
	ds_read_b128 v[190:193], v249 offset:22528
	buffer_load_dwordx4 v233, s[8:11], s19 offen lds
	s_mov_b32 m0, s30
	s_add_i32 s21, s19, 0x40000
	buffer_load_dwordx4 v235, s[8:11], s19 offen lds
	s_mov_b32 m0, s31
	s_nop 0
	buffer_load_dwordx4 v233, s[8:11], s21 offen lds
	s_mov_b32 m0, s35
	s_nop 0
	buffer_load_dwordx4 v235, s[8:11], s21 offen lds
	s_mov_b32 m0, s28
	s_nop 0
	buffer_load_dwordx4 v1, s[8:11], s20 offen lds
	s_mov_b32 m0, s38
	s_nop 0
	buffer_load_dwordx4 v234, s[8:11], s20 offen lds
	s_waitcnt vmcnt(8)
	s_waitcnt lgkmcnt(0)
	s_setprio 1
	s_barrier
	v_mfma_f32_16x16x32_bf16 v[10:13], v[130:133], v[162:165], v[10:13]
	v_mfma_f32_16x16x32_bf16 v[6:9], v[138:141], v[162:165], v[6:9]
	v_mfma_f32_16x16x32_bf16 v[2:5], v[130:133], v[166:169], v[2:5]
	v_mfma_f32_16x16x32_bf16 v[18:21], v[138:141], v[166:169], v[18:21]
	v_mfma_f32_16x16x32_bf16 v[14:17], v[130:133], v[178:181], v[14:17]
	v_mfma_f32_16x16x32_bf16 v[26:29], v[138:141], v[178:181], v[26:29]
	v_mfma_f32_16x16x32_bf16 v[22:25], v[130:133], v[182:185], v[22:25]
	v_mfma_f32_16x16x32_bf16 v[38:41], v[138:141], v[182:185], v[38:41]
	v_mfma_f32_16x16x32_bf16 v[10:13], v[134:137], v[170:173], v[10:13]
	v_mfma_f32_16x16x32_bf16 v[6:9], v[142:145], v[170:173], v[6:9]
	v_mfma_f32_16x16x32_bf16 v[2:5], v[134:137], v[174:177], v[2:5]
	v_mfma_f32_16x16x32_bf16 v[18:21], v[142:145], v[174:177], v[18:21]
	v_mfma_f32_16x16x32_bf16 v[14:17], v[134:137], v[186:189], v[14:17]
	v_mfma_f32_16x16x32_bf16 v[26:29], v[142:145], v[186:189], v[26:29]
	v_mfma_f32_16x16x32_bf16 v[22:25], v[134:137], v[190:193], v[22:25]
	v_mfma_f32_16x16x32_bf16 v[38:41], v[142:145], v[190:193], v[38:41]
	v_mfma_f32_16x16x32_bf16 v[34:37], v[146:149], v[162:165], v[34:37]
	v_mfma_f32_16x16x32_bf16 v[30:33], v[154:157], v[162:165], v[30:33]
	v_mfma_f32_16x16x32_bf16 v[42:45], v[146:149], v[166:169], v[42:45]
	v_mfma_f32_16x16x32_bf16 v[46:49], v[154:157], v[166:169], v[46:49]
	v_mfma_f32_16x16x32_bf16 v[50:53], v[146:149], v[178:181], v[50:53]
	v_mfma_f32_16x16x32_bf16 v[54:57], v[154:157], v[178:181], v[54:57]
	v_mfma_f32_16x16x32_bf16 v[58:61], v[146:149], v[182:185], v[58:61]
	v_mfma_f32_16x16x32_bf16 v[62:65], v[154:157], v[182:185], v[62:65]
	v_mfma_f32_16x16x32_bf16 v[34:37], v[150:153], v[170:173], v[34:37]
	v_mfma_f32_16x16x32_bf16 v[30:33], v[158:161], v[170:173], v[30:33]
	v_mfma_f32_16x16x32_bf16 v[42:45], v[150:153], v[174:177], v[42:45]
	v_mfma_f32_16x16x32_bf16 v[46:49], v[158:161], v[174:177], v[46:49]
	v_mfma_f32_16x16x32_bf16 v[50:53], v[150:153], v[186:189], v[50:53]
	v_mfma_f32_16x16x32_bf16 v[54:57], v[158:161], v[186:189], v[54:57]
	v_mfma_f32_16x16x32_bf16 v[58:61], v[150:153], v[190:193], v[58:61]
	v_mfma_f32_16x16x32_bf16 v[62:65], v[158:161], v[190:193], v[62:65]
	s_barrier
	s_setprio 0
	ds_read_b128 v[130:133], v194
	ds_read_b128 v[134:137], v195
	ds_read_b128 v[138:141], v196
	ds_read_b128 v[142:145], v197
	ds_read_b128 v[146:149], v198
	ds_read_b128 v[150:153], v199
	ds_read_b128 v[154:157], v200
	ds_read_b128 v[158:161], v201
	s_add_i32 s20, s20, 0x40000
	s_mov_b32 m0, s39
	ds_read_b128 v[162:165], v248 offset:32768
	ds_read_b128 v[166:169], v248 offset:34816
	ds_read_b128 v[170:173], v249 offset:32768
	ds_read_b128 v[174:177], v249 offset:34816
	ds_read_b128 v[178:181], v248 offset:36864
	ds_read_b128 v[182:185], v248 offset:38912
	ds_read_b128 v[186:189], v249 offset:36864
	ds_read_b128 v[190:193], v249 offset:38912
	buffer_load_dwordx4 v1, s[8:11], s20 offen lds
	s_mov_b32 m0, s41
	s_nop 0
	buffer_load_dwordx4 v234, s[8:11], s20 offen lds
	s_waitcnt vmcnt(8)
	s_waitcnt lgkmcnt(0)
	s_setprio 2
	v_mfma_f32_16x16x32_bf16 v[74:77], v[130:133], v[162:165], v[74:77]
	v_mfma_f32_16x16x32_bf16 v[70:73], v[138:141], v[162:165], v[70:73]
	v_mfma_f32_16x16x32_bf16 v[66:69], v[130:133], v[166:169], v[66:69]
	v_mfma_f32_16x16x32_bf16 v[82:85], v[138:141], v[166:169], v[82:85]
	s_barrier
	v_mfma_f32_16x16x32_bf16 v[78:81], v[130:133], v[178:181], v[78:81]
	v_mfma_f32_16x16x32_bf16 v[90:93], v[138:141], v[178:181], v[90:93]
	v_mfma_f32_16x16x32_bf16 v[86:89], v[130:133], v[182:185], v[86:89]
	v_mfma_f32_16x16x32_bf16 v[102:105], v[138:141], v[182:185], v[102:105]
	v_mfma_f32_16x16x32_bf16 v[74:77], v[134:137], v[170:173], v[74:77]
	v_mfma_f32_16x16x32_bf16 v[70:73], v[142:145], v[170:173], v[70:73]
	v_mfma_f32_16x16x32_bf16 v[66:69], v[134:137], v[174:177], v[66:69]
	v_mfma_f32_16x16x32_bf16 v[82:85], v[142:145], v[174:177], v[82:85]
	v_mfma_f32_16x16x32_bf16 v[78:81], v[134:137], v[186:189], v[78:81]
	v_mfma_f32_16x16x32_bf16 v[90:93], v[142:145], v[186:189], v[90:93]
	v_mfma_f32_16x16x32_bf16 v[86:89], v[134:137], v[190:193], v[86:89]
	v_mfma_f32_16x16x32_bf16 v[102:105], v[142:145], v[190:193], v[102:105]
	v_mfma_f32_16x16x32_bf16 v[98:101], v[146:149], v[162:165], v[98:101]
	v_mfma_f32_16x16x32_bf16 v[94:97], v[154:157], v[162:165], v[94:97]
	v_mfma_f32_16x16x32_bf16 v[106:109], v[146:149], v[166:169], v[106:109]
	v_mfma_f32_16x16x32_bf16 v[110:113], v[154:157], v[166:169], v[110:113]
	v_mfma_f32_16x16x32_bf16 v[114:117], v[146:149], v[178:181], v[114:117]
	v_mfma_f32_16x16x32_bf16 v[118:121], v[154:157], v[178:181], v[118:121]
	v_mfma_f32_16x16x32_bf16 v[122:125], v[146:149], v[182:185], v[122:125]
	v_mfma_f32_16x16x32_bf16 v[126:129], v[154:157], v[182:185], v[126:129]
	v_mfma_f32_16x16x32_bf16 v[98:101], v[150:153], v[170:173], v[98:101]
	v_mfma_f32_16x16x32_bf16 v[94:97], v[158:161], v[170:173], v[94:97]
	v_mfma_f32_16x16x32_bf16 v[106:109], v[150:153], v[174:177], v[106:109]
	v_mfma_f32_16x16x32_bf16 v[110:113], v[158:161], v[174:177], v[110:113]
	v_mfma_f32_16x16x32_bf16 v[114:117], v[150:153], v[186:189], v[114:117]
	v_mfma_f32_16x16x32_bf16 v[118:121], v[158:161], v[186:189], v[118:121]
	v_mfma_f32_16x16x32_bf16 v[122:125], v[150:153], v[190:193], v[122:125]
	v_mfma_f32_16x16x32_bf16 v[126:129], v[158:161], v[190:193], v[126:129]
	s_barrier
	s_setprio 0
	s_mov_b32 m0, s44
	s_add_i32 s20, s19, 0x80
	ds_read_b128 v[162:165], v248 offset:49152
	ds_read_b128 v[166:169], v248 offset:51200
	ds_read_b128 v[170:173], v249 offset:49152
	ds_read_b128 v[174:177], v249 offset:51200
	ds_read_b128 v[178:181], v248 offset:53248
	ds_read_b128 v[182:185], v248 offset:55296
	ds_read_b128 v[186:189], v249 offset:53248
	ds_read_b128 v[190:193], v249 offset:55296
	buffer_load_dwordx4 v233, s[8:11], s20 offen lds
	s_mov_b32 m0, s45
	s_add_i32 s19, s19, 0x40080
	buffer_load_dwordx4 v235, s[8:11], s20 offen lds
	s_mov_b32 m0, s48
	s_nop 0
	buffer_load_dwordx4 v233, s[8:11], s19 offen lds
	s_mov_b32 m0, s49
	s_nop 0
	buffer_load_dwordx4 v235, s[8:11], s19 offen lds
	s_mov_b32 m0, s46
	s_nop 0
	buffer_load_dwordx4 v1, s[8:11], s18 offen lds
	s_mov_b32 m0, s47
	s_nop 0
	buffer_load_dwordx4 v234, s[8:11], s18 offen lds
	s_waitcnt vmcnt(8)
	s_waitcnt lgkmcnt(0)
	s_setprio 1
	s_barrier
	v_mfma_f32_16x16x32_bf16 v[10:13], v[130:133], v[162:165], v[10:13]
	v_mfma_f32_16x16x32_bf16 v[6:9], v[138:141], v[162:165], v[6:9]
	v_mfma_f32_16x16x32_bf16 v[2:5], v[130:133], v[166:169], v[2:5]
	v_mfma_f32_16x16x32_bf16 v[18:21], v[138:141], v[166:169], v[18:21]
	v_mfma_f32_16x16x32_bf16 v[14:17], v[130:133], v[178:181], v[14:17]
	v_mfma_f32_16x16x32_bf16 v[26:29], v[138:141], v[178:181], v[26:29]
	v_mfma_f32_16x16x32_bf16 v[22:25], v[130:133], v[182:185], v[22:25]
	v_mfma_f32_16x16x32_bf16 v[38:41], v[138:141], v[182:185], v[38:41]
	v_mfma_f32_16x16x32_bf16 v[10:13], v[134:137], v[170:173], v[10:13]
	v_mfma_f32_16x16x32_bf16 v[6:9], v[142:145], v[170:173], v[6:9]
	v_mfma_f32_16x16x32_bf16 v[2:5], v[134:137], v[174:177], v[2:5]
	v_mfma_f32_16x16x32_bf16 v[18:21], v[142:145], v[174:177], v[18:21]
	v_mfma_f32_16x16x32_bf16 v[14:17], v[134:137], v[186:189], v[14:17]
	v_mfma_f32_16x16x32_bf16 v[26:29], v[142:145], v[186:189], v[26:29]
	v_mfma_f32_16x16x32_bf16 v[22:25], v[134:137], v[190:193], v[22:25]
	v_mfma_f32_16x16x32_bf16 v[38:41], v[142:145], v[190:193], v[38:41]
	v_mfma_f32_16x16x32_bf16 v[34:37], v[146:149], v[162:165], v[34:37]
	v_mfma_f32_16x16x32_bf16 v[30:33], v[154:157], v[162:165], v[30:33]
	v_mfma_f32_16x16x32_bf16 v[42:45], v[146:149], v[166:169], v[42:45]
	v_mfma_f32_16x16x32_bf16 v[46:49], v[154:157], v[166:169], v[46:49]
	v_mfma_f32_16x16x32_bf16 v[50:53], v[146:149], v[178:181], v[50:53]
	v_mfma_f32_16x16x32_bf16 v[54:57], v[154:157], v[178:181], v[54:57]
	v_mfma_f32_16x16x32_bf16 v[58:61], v[146:149], v[182:185], v[58:61]
	v_mfma_f32_16x16x32_bf16 v[62:65], v[154:157], v[182:185], v[62:65]
	v_mfma_f32_16x16x32_bf16 v[34:37], v[150:153], v[170:173], v[34:37]
	v_mfma_f32_16x16x32_bf16 v[30:33], v[158:161], v[170:173], v[30:33]
	v_mfma_f32_16x16x32_bf16 v[42:45], v[150:153], v[174:177], v[42:45]
	v_mfma_f32_16x16x32_bf16 v[46:49], v[158:161], v[174:177], v[46:49]
	v_mfma_f32_16x16x32_bf16 v[50:53], v[150:153], v[186:189], v[50:53]
	v_mfma_f32_16x16x32_bf16 v[54:57], v[158:161], v[186:189], v[54:57]
	v_mfma_f32_16x16x32_bf16 v[58:61], v[150:153], v[190:193], v[58:61]
	v_mfma_f32_16x16x32_bf16 v[62:65], v[158:161], v[190:193], v[62:65]
	s_barrier
	s_setprio 0
	s_add_i32 s4, s4, 2
	s_addk_i32 s5, 0x100
	s_cmp_gt_u32 s4, 13
	s_cbranch_scc0 .LBB0_841
	s_and_b64 vcc, exec, s[16:17]
	s_cbranch_vccz .LBB0_844
	s_barrier

.LBB0_1122:
	ds_read_b128 v[130:133], v240
	ds_read_b128 v[134:137], v241
	ds_read_b128 v[138:141], v242
	ds_read_b128 v[142:145], v243
	ds_read_b128 v[146:149], v244
	ds_read_b128 v[150:153], v245
	ds_read_b128 v[154:157], v246
	ds_read_b128 v[158:161], v247
	s_add_i32 s8, s31, s53
	s_add_i32 s55, s26, s53
	s_add_i32 s54, s8, 0x800
	s_addk_i32 s55, 0x800
	s_cmp_eq_u32 s53, 0
	s_cselect_b32 s56, s4, s54
	s_cselect_b32 s55, s5, s55
	s_add_i32 s54, s56, 0x80
	s_add_i32 s57, s8, 0x40780
	s_mov_b32 s8, s70
	s_mov_b32 m0, s44
	ds_read_b128 v[162:165], v248
	ds_read_b128 v[166:169], v248 offset:2048
	ds_read_b128 v[170:173], v249
	ds_read_b128 v[174:177], v249 offset:2048
	ds_read_b128 v[178:181], v248 offset:4096
	ds_read_b128 v[182:185], v248 offset:6144
	ds_read_b128 v[186:189], v249 offset:4096
	ds_read_b128 v[190:193], v249 offset:6144
	buffer_load_dwordx4 v1, s[8:11], s57 offen lds
	s_mov_b32 m0, s45
	s_nop 0
	buffer_load_dwordx4 v234, s[8:11], s57 offen lds
	s_waitcnt vmcnt(8)
	s_waitcnt lgkmcnt(0)
	s_setprio 2
	v_mfma_f32_16x16x32_bf16 v[126:129], v[130:133], v[162:165], v[126:129]
	v_mfma_f32_16x16x32_bf16 v[122:125], v[138:141], v[162:165], v[122:125]
	v_mfma_f32_16x16x32_bf16 v[118:121], v[130:133], v[166:169], v[118:121]
	v_mfma_f32_16x16x32_bf16 v[114:117], v[138:141], v[166:169], v[114:117]
	s_barrier
	v_mfma_f32_16x16x32_bf16 v[110:113], v[130:133], v[178:181], v[110:113]
	v_mfma_f32_16x16x32_bf16 v[106:109], v[138:141], v[178:181], v[106:109]
	v_mfma_f32_16x16x32_bf16 v[102:105], v[130:133], v[182:185], v[102:105]
	v_mfma_f32_16x16x32_bf16 v[98:101], v[138:141], v[182:185], v[98:101]
	v_mfma_f32_16x16x32_bf16 v[126:129], v[134:137], v[170:173], v[126:129]
	v_mfma_f32_16x16x32_bf16 v[122:125], v[142:145], v[170:173], v[122:125]
	v_mfma_f32_16x16x32_bf16 v[118:121], v[134:137], v[174:177], v[118:121]
	v_mfma_f32_16x16x32_bf16 v[114:117], v[142:145], v[174:177], v[114:117]
	v_mfma_f32_16x16x32_bf16 v[110:113], v[134:137], v[186:189], v[110:113]
	v_mfma_f32_16x16x32_bf16 v[106:109], v[142:145], v[186:189], v[106:109]
	v_mfma_f32_16x16x32_bf16 v[102:105], v[134:137], v[190:193], v[102:105]
	v_mfma_f32_16x16x32_bf16 v[98:101], v[142:145], v[190:193], v[98:101]
	v_mfma_f32_16x16x32_bf16 v[94:97], v[146:149], v[162:165], v[94:97]
	v_mfma_f32_16x16x32_bf16 v[90:93], v[154:157], v[162:165], v[90:93]
	v_mfma_f32_16x16x32_bf16 v[86:89], v[146:149], v[166:169], v[86:89]
	v_mfma_f32_16x16x32_bf16 v[82:85], v[154:157], v[166:169], v[82:85]
	v_mfma_f32_16x16x32_bf16 v[78:81], v[146:149], v[178:181], v[78:81]
	v_mfma_f32_16x16x32_bf16 v[74:77], v[154:157], v[178:181], v[74:77]
	v_mfma_f32_16x16x32_bf16 v[70:73], v[146:149], v[182:185], v[70:73]
	v_mfma_f32_16x16x32_bf16 v[66:69], v[154:157], v[182:185], v[66:69]
	v_mfma_f32_16x16x32_bf16 v[94:97], v[150:153], v[170:173], v[94:97]
	v_mfma_f32_16x16x32_bf16 v[90:93], v[158:161], v[170:173], v[90:93]
	v_mfma_f32_16x16x32_bf16 v[86:89], v[150:153], v[174:177], v[86:89]
	v_mfma_f32_16x16x32_bf16 v[82:85], v[158:161], v[174:177], v[82:85]
	v_mfma_f32_16x16x32_bf16 v[78:81], v[150:153], v[186:189], v[78:81]
	v_mfma_f32_16x16x32_bf16 v[74:77], v[158:161], v[186:189], v[74:77]
	v_mfma_f32_16x16x32_bf16 v[70:73], v[150:153], v[190:193], v[70:73]
	v_mfma_f32_16x16x32_bf16 v[66:69], v[158:161], v[190:193], v[66:69]
	s_barrier
	s_setprio 0
	s_mov_b32 m0, s23
	ds_read_b128 v[162:165], v248 offset:16384
	ds_read_b128 v[166:169], v248 offset:18432
	ds_read_b128 v[170:173], v249 offset:16384
	ds_read_b128 v[174:177], v249 offset:18432
	ds_read_b128 v[178:181], v248 offset:20480
	ds_read_b128 v[182:185], v248 offset:22528
	ds_read_b128 v[186:189], v249 offset:20480
	ds_read_b128 v[190:193], v249 offset:22528
	buffer_load_dwordx4 v233, s[8:11], s55 offen lds
	s_mov_b32 m0, s24
	s_add_i32 s57, s55, 0x40000
	buffer_load_dwordx4 v235, s[8:11], s55 offen lds
	s_mov_b32 m0, s25
	s_nop 0
	buffer_load_dwordx4 v233, s[8:11], s57 offen lds
	s_mov_b32 m0, s27
	s_nop 0
	buffer_load_dwordx4 v235, s[8:11], s57 offen lds
	s_mov_b32 m0, s22
	s_nop 0
	buffer_load_dwordx4 v1, s[8:11], s56 offen lds
	s_mov_b32 m0, s28
	s_nop 0
	buffer_load_dwordx4 v234, s[8:11], s56 offen lds
	s_waitcnt vmcnt(8)
	s_waitcnt lgkmcnt(0)
	s_setprio 1
	s_barrier
	v_mfma_f32_16x16x32_bf16 v[62:65], v[130:133], v[162:165], v[62:65]
	v_mfma_f32_16x16x32_bf16 v[58:61], v[138:141], v[162:165], v[58:61]
	v_mfma_f32_16x16x32_bf16 v[54:57], v[130:133], v[166:169], v[54:57]
	v_mfma_f32_16x16x32_bf16 v[50:53], v[138:141], v[166:169], v[50:53]
	v_mfma_f32_16x16x32_bf16 v[46:49], v[130:133], v[178:181], v[46:49]
	v_mfma_f32_16x16x32_bf16 v[42:45], v[138:141], v[178:181], v[42:45]
	v_mfma_f32_16x16x32_bf16 v[38:41], v[130:133], v[182:185], v[38:41]
	v_mfma_f32_16x16x32_bf16 v[34:37], v[138:141], v[182:185], v[34:37]
	v_mfma_f32_16x16x32_bf16 v[62:65], v[134:137], v[170:173], v[62:65]
	v_mfma_f32_16x16x32_bf16 v[58:61], v[142:145], v[170:173], v[58:61]
	v_mfma_f32_16x16x32_bf16 v[54:57], v[134:137], v[174:177], v[54:57]
	v_mfma_f32_16x16x32_bf16 v[50:53], v[142:145], v[174:177], v[50:53]
	v_mfma_f32_16x16x32_bf16 v[46:49], v[134:137], v[186:189], v[46:49]
	v_mfma_f32_16x16x32_bf16 v[42:45], v[142:145], v[186:189], v[42:45]
	v_mfma_f32_16x16x32_bf16 v[38:41], v[134:137], v[190:193], v[38:41]
	v_mfma_f32_16x16x32_bf16 v[34:37], v[142:145], v[190:193], v[34:37]
	v_mfma_f32_16x16x32_bf16 v[30:33], v[146:149], v[162:165], v[30:33]
	v_mfma_f32_16x16x32_bf16 v[26:29], v[154:157], v[162:165], v[26:29]
	v_mfma_f32_16x16x32_bf16 v[22:25], v[146:149], v[166:169], v[22:25]
	v_mfma_f32_16x16x32_bf16 v[18:21], v[154:157], v[166:169], v[18:21]
	v_mfma_f32_16x16x32_bf16 v[14:17], v[146:149], v[178:181], v[14:17]
	v_mfma_f32_16x16x32_bf16 v[10:13], v[154:157], v[178:181], v[10:13]
	v_mfma_f32_16x16x32_bf16 v[6:9], v[146:149], v[182:185], v[6:9]
	v_mfma_f32_16x16x32_bf16 v[2:5], v[154:157], v[182:185], v[2:5]
	v_mfma_f32_16x16x32_bf16 v[30:33], v[150:153], v[170:173], v[30:33]
	v_mfma_f32_16x16x32_bf16 v[26:29], v[158:161], v[170:173], v[26:29]
	v_mfma_f32_16x16x32_bf16 v[22:25], v[150:153], v[174:177], v[22:25]
	v_mfma_f32_16x16x32_bf16 v[18:21], v[158:161], v[174:177], v[18:21]
	v_mfma_f32_16x16x32_bf16 v[14:17], v[150:153], v[186:189], v[14:17]
	v_mfma_f32_16x16x32_bf16 v[10:13], v[158:161], v[186:189], v[10:13]
	v_mfma_f32_16x16x32_bf16 v[6:9], v[150:153], v[190:193], v[6:9]
	v_mfma_f32_16x16x32_bf16 v[2:5], v[158:161], v[190:193], v[2:5]
	s_barrier
	s_setprio 0
	ds_read_b128 v[130:133], v194
	ds_read_b128 v[134:137], v195
	ds_read_b128 v[138:141], v196
	ds_read_b128 v[142:145], v197
	ds_read_b128 v[146:149], v198
	ds_read_b128 v[150:153], v199
	ds_read_b128 v[154:157], v200
	ds_read_b128 v[158:161], v201
	s_add_i32 s56, s56, 0x40000
	s_mov_b32 m0, s29
	ds_read_b128 v[162:165], v248 offset:32768
	ds_read_b128 v[166:169], v248 offset:34816
	ds_read_b128 v[170:173], v249 offset:32768
	ds_read_b128 v[174:177], v249 offset:34816
	ds_read_b128 v[178:181], v248 offset:36864
	ds_read_b128 v[182:185], v248 offset:38912
	ds_read_b128 v[186:189], v249 offset:36864
	ds_read_b128 v[190:193], v249 offset:38912
	buffer_load_dwordx4 v1, s[8:11], s56 offen lds
	s_mov_b32 m0, s30
	s_nop 0
	buffer_load_dwordx4 v234, s[8:11], s56 offen lds
	s_waitcnt vmcnt(8)
	s_waitcnt lgkmcnt(0)
	s_setprio 2
	v_mfma_f32_16x16x32_bf16 v[126:129], v[130:133], v[162:165], v[126:129]
	v_mfma_f32_16x16x32_bf16 v[122:125], v[138:141], v[162:165], v[122:125]
	v_mfma_f32_16x16x32_bf16 v[118:121], v[130:133], v[166:169], v[118:121]
	v_mfma_f32_16x16x32_bf16 v[114:117], v[138:141], v[166:169], v[114:117]
	s_barrier
	v_mfma_f32_16x16x32_bf16 v[110:113], v[130:133], v[178:181], v[110:113]
	v_mfma_f32_16x16x32_bf16 v[106:109], v[138:141], v[178:181], v[106:109]
	v_mfma_f32_16x16x32_bf16 v[102:105], v[130:133], v[182:185], v[102:105]
	v_mfma_f32_16x16x32_bf16 v[98:101], v[138:141], v[182:185], v[98:101]
	v_mfma_f32_16x16x32_bf16 v[126:129], v[134:137], v[170:173], v[126:129]
	v_mfma_f32_16x16x32_bf16 v[122:125], v[142:145], v[170:173], v[122:125]
	v_mfma_f32_16x16x32_bf16 v[118:121], v[134:137], v[174:177], v[118:121]
	v_mfma_f32_16x16x32_bf16 v[114:117], v[142:145], v[174:177], v[114:117]
	v_mfma_f32_16x16x32_bf16 v[110:113], v[134:137], v[186:189], v[110:113]
	v_mfma_f32_16x16x32_bf16 v[106:109], v[142:145], v[186:189], v[106:109]
	v_mfma_f32_16x16x32_bf16 v[102:105], v[134:137], v[190:193], v[102:105]
	v_mfma_f32_16x16x32_bf16 v[98:101], v[142:145], v[190:193], v[98:101]
	v_mfma_f32_16x16x32_bf16 v[94:97], v[146:149], v[162:165], v[94:97]
	v_mfma_f32_16x16x32_bf16 v[90:93], v[154:157], v[162:165], v[90:93]
	v_mfma_f32_16x16x32_bf16 v[86:89], v[146:149], v[166:169], v[86:89]
	v_mfma_f32_16x16x32_bf16 v[82:85], v[154:157], v[166:169], v[82:85]
	v_mfma_f32_16x16x32_bf16 v[78:81], v[146:149], v[178:181], v[78:81]
	v_mfma_f32_16x16x32_bf16 v[74:77], v[154:157], v[178:181], v[74:77]
	v_mfma_f32_16x16x32_bf16 v[70:73], v[146:149], v[182:185], v[70:73]
	v_mfma_f32_16x16x32_bf16 v[66:69], v[154:157], v[182:185], v[66:69]
	v_mfma_f32_16x16x32_bf16 v[94:97], v[150:153], v[170:173], v[94:97]
	v_mfma_f32_16x16x32_bf16 v[90:93], v[158:161], v[170:173], v[90:93]
	v_mfma_f32_16x16x32_bf16 v[86:89], v[150:153], v[174:177], v[86:89]
	v_mfma_f32_16x16x32_bf16 v[82:85], v[158:161], v[174:177], v[82:85]
	v_mfma_f32_16x16x32_bf16 v[78:81], v[150:153], v[186:189], v[78:81]
	v_mfma_f32_16x16x32_bf16 v[74:77], v[158:161], v[186:189], v[74:77]
	v_mfma_f32_16x16x32_bf16 v[70:73], v[150:153], v[190:193], v[70:73]
	v_mfma_f32_16x16x32_bf16 v[66:69], v[158:161], v[190:193], v[66:69]
	s_barrier
	s_setprio 0
	s_mov_b32 m0, s35
	s_add_i32 s56, s55, 0x80
	ds_read_b128 v[162:165], v248 offset:49152
	ds_read_b128 v[166:169], v248 offset:51200
	ds_read_b128 v[170:173], v249 offset:49152
	ds_read_b128 v[174:177], v249 offset:51200
	ds_read_b128 v[178:181], v248 offset:53248
	ds_read_b128 v[182:185], v248 offset:55296
	ds_read_b128 v[186:189], v249 offset:53248
	ds_read_b128 v[190:193], v249 offset:55296
	buffer_load_dwordx4 v233, s[8:11], s56 offen lds
	s_mov_b32 m0, s36
	s_add_i32 s55, s55, 0x40080
	buffer_load_dwordx4 v235, s[8:11], s56 offen lds
	s_mov_b32 m0, s39
	s_nop 0
	buffer_load_dwordx4 v233, s[8:11], s55 offen lds
	s_mov_b32 m0, s41
	s_nop 0
	buffer_load_dwordx4 v235, s[8:11], s55 offen lds
	s_mov_b32 m0, s37
	s_nop 0
	buffer_load_dwordx4 v1, s[8:11], s54 offen lds
	s_mov_b32 m0, s38
	s_nop 0
	buffer_load_dwordx4 v234, s[8:11], s54 offen lds
	s_waitcnt vmcnt(8)
	s_waitcnt lgkmcnt(0)
	s_setprio 1
	s_barrier
	v_mfma_f32_16x16x32_bf16 v[62:65], v[130:133], v[162:165], v[62:65]
	v_mfma_f32_16x16x32_bf16 v[58:61], v[138:141], v[162:165], v[58:61]
	v_mfma_f32_16x16x32_bf16 v[54:57], v[130:133], v[166:169], v[54:57]
	v_mfma_f32_16x16x32_bf16 v[50:53], v[138:141], v[166:169], v[50:53]
	v_mfma_f32_16x16x32_bf16 v[46:49], v[130:133], v[178:181], v[46:49]
	v_mfma_f32_16x16x32_bf16 v[42:45], v[138:141], v[178:181], v[42:45]
	v_mfma_f32_16x16x32_bf16 v[38:41], v[130:133], v[182:185], v[38:41]
	v_mfma_f32_16x16x32_bf16 v[34:37], v[138:141], v[182:185], v[34:37]
	v_mfma_f32_16x16x32_bf16 v[62:65], v[134:137], v[170:173], v[62:65]
	v_mfma_f32_16x16x32_bf16 v[58:61], v[142:145], v[170:173], v[58:61]
	v_mfma_f32_16x16x32_bf16 v[54:57], v[134:137], v[174:177], v[54:57]
	v_mfma_f32_16x16x32_bf16 v[50:53], v[142:145], v[174:177], v[50:53]
	v_mfma_f32_16x16x32_bf16 v[46:49], v[134:137], v[186:189], v[46:49]
	v_mfma_f32_16x16x32_bf16 v[42:45], v[142:145], v[186:189], v[42:45]
	v_mfma_f32_16x16x32_bf16 v[38:41], v[134:137], v[190:193], v[38:41]
	v_mfma_f32_16x16x32_bf16 v[34:37], v[142:145], v[190:193], v[34:37]
	v_mfma_f32_16x16x32_bf16 v[30:33], v[146:149], v[162:165], v[30:33]
	v_mfma_f32_16x16x32_bf16 v[26:29], v[154:157], v[162:165], v[26:29]
	v_mfma_f32_16x16x32_bf16 v[22:25], v[146:149], v[166:169], v[22:25]
	v_mfma_f32_16x16x32_bf16 v[18:21], v[154:157], v[166:169], v[18:21]
	v_mfma_f32_16x16x32_bf16 v[14:17], v[146:149], v[178:181], v[14:17]
	v_mfma_f32_16x16x32_bf16 v[10:13], v[154:157], v[178:181], v[10:13]
	v_mfma_f32_16x16x32_bf16 v[6:9], v[146:149], v[182:185], v[6:9]
	v_mfma_f32_16x16x32_bf16 v[2:5], v[154:157], v[182:185], v[2:5]
	v_mfma_f32_16x16x32_bf16 v[30:33], v[150:153], v[170:173], v[30:33]
	v_mfma_f32_16x16x32_bf16 v[26:29], v[158:161], v[170:173], v[26:29]
	v_mfma_f32_16x16x32_bf16 v[22:25], v[150:153], v[174:177], v[22:25]
	v_mfma_f32_16x16x32_bf16 v[18:21], v[158:161], v[174:177], v[18:21]
	v_mfma_f32_16x16x32_bf16 v[14:17], v[150:153], v[186:189], v[14:17]
	v_mfma_f32_16x16x32_bf16 v[10:13], v[158:161], v[186:189], v[10:13]
	v_mfma_f32_16x16x32_bf16 v[6:9], v[150:153], v[190:193], v[6:9]
	v_mfma_f32_16x16x32_bf16 v[2:5], v[158:161], v[190:193], v[2:5]
	s_barrier
	s_setprio 0
	s_add_i32 s33, s33, 2
	s_addk_i32 s53, 0x100
	s_cmp_gt_u32 s33, 13
	s_cbranch_scc0 .LBB0_1122
	s_and_b64 vcc, exec, s[16:17]
	s_cbranch_vccz .LBB0_1125
	s_barrier

.LBB0_1251:
	ds_read_b128 v[130:133], v239
	ds_read_b128 v[134:137], v240
	ds_read_b128 v[138:141], v241
	ds_read_b128 v[142:145], v242
	ds_read_b128 v[146:149], v243
	ds_read_b128 v[150:153], v244
	ds_read_b128 v[154:157], v245
	ds_read_b128 v[158:161], v246
	s_add_i32 s8, s51, s5
	s_add_i32 s31, s46, s5
	s_add_i32 s30, s8, 0x2000
	s_addk_i32 s31, 0x2000
	s_cmp_eq_u32 s5, 0
	s_cselect_b32 s33, s0, s30
	s_cselect_b32 s31, s1, s31
	s_add_i32 s30, s33, 0x80
	s_add_i32 s34, s8, 0x101f80
	s_mov_b32 s8, s70
	s_mov_b32 m0, s61
	ds_read_b128 v[162:165], v247
	ds_read_b128 v[166:169], v247 offset:2048
	ds_read_b128 v[170:173], v248
	ds_read_b128 v[174:177], v248 offset:2048
	ds_read_b128 v[178:181], v247 offset:4096
	ds_read_b128 v[182:185], v247 offset:6144
	ds_read_b128 v[186:189], v248 offset:4096
	ds_read_b128 v[190:193], v248 offset:6144
	buffer_load_dwordx4 v230, s[8:11], s34 offen lds
	s_mov_b32 m0, s64
	s_nop 0
	buffer_load_dwordx4 v233, s[8:11], s34 offen lds
	s_waitcnt vmcnt(8)
	s_waitcnt lgkmcnt(0)
	s_setprio 2
	v_mfma_f32_16x16x32_bf16 v[74:77], v[130:133], v[162:165], v[74:77]
	v_mfma_f32_16x16x32_bf16 v[70:73], v[138:141], v[162:165], v[70:73]
	v_mfma_f32_16x16x32_bf16 v[66:69], v[130:133], v[166:169], v[66:69]
	v_mfma_f32_16x16x32_bf16 v[82:85], v[138:141], v[166:169], v[82:85]
	s_barrier
	v_mfma_f32_16x16x32_bf16 v[78:81], v[130:133], v[178:181], v[78:81]
	v_mfma_f32_16x16x32_bf16 v[90:93], v[138:141], v[178:181], v[90:93]
	v_mfma_f32_16x16x32_bf16 v[86:89], v[130:133], v[182:185], v[86:89]
	v_mfma_f32_16x16x32_bf16 v[102:105], v[138:141], v[182:185], v[102:105]
	v_mfma_f32_16x16x32_bf16 v[74:77], v[134:137], v[170:173], v[74:77]
	v_mfma_f32_16x16x32_bf16 v[70:73], v[142:145], v[170:173], v[70:73]
	v_mfma_f32_16x16x32_bf16 v[66:69], v[134:137], v[174:177], v[66:69]
	v_mfma_f32_16x16x32_bf16 v[82:85], v[142:145], v[174:177], v[82:85]
	v_mfma_f32_16x16x32_bf16 v[78:81], v[134:137], v[186:189], v[78:81]
	v_mfma_f32_16x16x32_bf16 v[90:93], v[142:145], v[186:189], v[90:93]
	v_mfma_f32_16x16x32_bf16 v[86:89], v[134:137], v[190:193], v[86:89]
	v_mfma_f32_16x16x32_bf16 v[102:105], v[142:145], v[190:193], v[102:105]
	v_mfma_f32_16x16x32_bf16 v[98:101], v[146:149], v[162:165], v[98:101]
	v_mfma_f32_16x16x32_bf16 v[94:97], v[154:157], v[162:165], v[94:97]
	v_mfma_f32_16x16x32_bf16 v[106:109], v[146:149], v[166:169], v[106:109]
	v_mfma_f32_16x16x32_bf16 v[110:113], v[154:157], v[166:169], v[110:113]
	v_mfma_f32_16x16x32_bf16 v[114:117], v[146:149], v[178:181], v[114:117]
	v_mfma_f32_16x16x32_bf16 v[118:121], v[154:157], v[178:181], v[118:121]
	v_mfma_f32_16x16x32_bf16 v[122:125], v[146:149], v[182:185], v[122:125]
	v_mfma_f32_16x16x32_bf16 v[126:129], v[154:157], v[182:185], v[126:129]
	v_mfma_f32_16x16x32_bf16 v[98:101], v[150:153], v[170:173], v[98:101]
	v_mfma_f32_16x16x32_bf16 v[94:97], v[158:161], v[170:173], v[94:97]
	v_mfma_f32_16x16x32_bf16 v[106:109], v[150:153], v[174:177], v[106:109]
	v_mfma_f32_16x16x32_bf16 v[110:113], v[158:161], v[174:177], v[110:113]
	v_mfma_f32_16x16x32_bf16 v[114:117], v[150:153], v[186:189], v[114:117]
	v_mfma_f32_16x16x32_bf16 v[118:121], v[158:161], v[186:189], v[118:121]
	v_mfma_f32_16x16x32_bf16 v[122:125], v[150:153], v[190:193], v[122:125]
	v_mfma_f32_16x16x32_bf16 v[126:129], v[158:161], v[190:193], v[126:129]
	s_barrier
	s_setprio 0
	s_mov_b32 m0, s43
	ds_read_b128 v[162:165], v247 offset:16384
	ds_read_b128 v[166:169], v247 offset:18432
	ds_read_b128 v[170:173], v248 offset:16384
	ds_read_b128 v[174:177], v248 offset:18432
	ds_read_b128 v[178:181], v247 offset:20480
	ds_read_b128 v[182:185], v247 offset:22528
	ds_read_b128 v[186:189], v248 offset:20480
	ds_read_b128 v[190:193], v248 offset:22528
	buffer_load_dwordx4 v231, s[8:11], s31 offen lds
	s_mov_b32 m0, s44
	s_add_i32 s34, s31, 0x100000
	buffer_load_dwordx4 v234, s[8:11], s31 offen lds
	s_mov_b32 m0, s45
	s_nop 0
	buffer_load_dwordx4 v231, s[8:11], s34 offen lds
	s_mov_b32 m0, s47
	s_nop 0
	buffer_load_dwordx4 v234, s[8:11], s34 offen lds
	s_mov_b32 m0, s42
	s_nop 0
	buffer_load_dwordx4 v230, s[8:11], s33 offen lds
	s_mov_b32 m0, s48
	s_nop 0
	buffer_load_dwordx4 v233, s[8:11], s33 offen lds
	s_waitcnt vmcnt(8)
	s_waitcnt lgkmcnt(0)
	s_setprio 1
	s_barrier
	v_mfma_f32_16x16x32_bf16 v[10:13], v[130:133], v[162:165], v[10:13]
	v_mfma_f32_16x16x32_bf16 v[6:9], v[138:141], v[162:165], v[6:9]
	v_mfma_f32_16x16x32_bf16 v[0:3], v[130:133], v[166:169], v[2:5]
	v_mfma_f32_16x16x32_bf16 v[18:21], v[138:141], v[166:169], v[18:21]
	v_mfma_f32_16x16x32_bf16 v[14:17], v[130:133], v[178:181], v[14:17]
	v_mfma_f32_16x16x32_bf16 v[26:29], v[138:141], v[178:181], v[26:29]
	v_mfma_f32_16x16x32_bf16 v[22:25], v[130:133], v[182:185], v[22:25]
	v_mfma_f32_16x16x32_bf16 v[38:41], v[138:141], v[182:185], v[38:41]
	v_mfma_f32_16x16x32_bf16 v[10:13], v[134:137], v[170:173], v[10:13]
	v_mfma_f32_16x16x32_bf16 v[6:9], v[142:145], v[170:173], v[6:9]
	v_mfma_f32_16x16x32_bf16 v[0:3], v[134:137], v[174:177], v[0:3]
	v_mfma_f32_16x16x32_bf16 v[18:21], v[142:145], v[174:177], v[18:21]
	v_mfma_f32_16x16x32_bf16 v[14:17], v[134:137], v[186:189], v[14:17]
	v_mfma_f32_16x16x32_bf16 v[26:29], v[142:145], v[186:189], v[26:29]
	v_mfma_f32_16x16x32_bf16 v[22:25], v[134:137], v[190:193], v[22:25]
	v_mfma_f32_16x16x32_bf16 v[38:41], v[142:145], v[190:193], v[38:41]
	v_mfma_f32_16x16x32_bf16 v[34:37], v[146:149], v[162:165], v[34:37]
	v_mfma_f32_16x16x32_bf16 v[30:33], v[154:157], v[162:165], v[30:33]
	v_mfma_f32_16x16x32_bf16 v[42:45], v[146:149], v[166:169], v[42:45]
	v_mfma_f32_16x16x32_bf16 v[46:49], v[154:157], v[166:169], v[46:49]
	v_mfma_f32_16x16x32_bf16 v[50:53], v[146:149], v[178:181], v[50:53]
	v_mfma_f32_16x16x32_bf16 v[54:57], v[154:157], v[178:181], v[54:57]
	v_mfma_f32_16x16x32_bf16 v[58:61], v[146:149], v[182:185], v[58:61]
	v_mfma_f32_16x16x32_bf16 v[62:65], v[154:157], v[182:185], v[62:65]
	v_mfma_f32_16x16x32_bf16 v[34:37], v[150:153], v[170:173], v[34:37]
	v_mfma_f32_16x16x32_bf16 v[30:33], v[158:161], v[170:173], v[30:33]
	v_mfma_f32_16x16x32_bf16 v[42:45], v[150:153], v[174:177], v[42:45]
	v_mfma_f32_16x16x32_bf16 v[46:49], v[158:161], v[174:177], v[46:49]
	v_mfma_f32_16x16x32_bf16 v[50:53], v[150:153], v[186:189], v[50:53]
	v_mfma_f32_16x16x32_bf16 v[54:57], v[158:161], v[186:189], v[54:57]
	v_mfma_f32_16x16x32_bf16 v[58:61], v[150:153], v[190:193], v[58:61]
	v_mfma_f32_16x16x32_bf16 v[62:65], v[158:161], v[190:193], v[62:65]
	s_barrier
	s_setprio 0
	ds_read_b128 v[130:133], v194
	ds_read_b128 v[134:137], v195
	ds_read_b128 v[138:141], v196
	ds_read_b128 v[142:145], v197
	ds_read_b128 v[146:149], v198
	ds_read_b128 v[150:153], v199
	ds_read_b128 v[154:157], v200
	ds_read_b128 v[158:161], v201
	s_add_i32 s33, s33, 0x100000
	s_mov_b32 m0, s49
	ds_read_b128 v[162:165], v247 offset:32768
	ds_read_b128 v[166:169], v247 offset:34816
	ds_read_b128 v[170:173], v248 offset:32768
	ds_read_b128 v[174:177], v248 offset:34816
	ds_read_b128 v[178:181], v247 offset:36864
	ds_read_b128 v[182:185], v247 offset:38912
	ds_read_b128 v[186:189], v248 offset:36864
	ds_read_b128 v[190:193], v248 offset:38912
	buffer_load_dwordx4 v230, s[8:11], s33 offen lds
	s_mov_b32 m0, s50
	s_nop 0
	buffer_load_dwordx4 v233, s[8:11], s33 offen lds
	s_waitcnt vmcnt(8)
	s_waitcnt lgkmcnt(0)
	s_setprio 2
	v_mfma_f32_16x16x32_bf16 v[74:77], v[130:133], v[162:165], v[74:77]
	v_mfma_f32_16x16x32_bf16 v[70:73], v[138:141], v[162:165], v[70:73]
	v_mfma_f32_16x16x32_bf16 v[66:69], v[130:133], v[166:169], v[66:69]
	v_mfma_f32_16x16x32_bf16 v[82:85], v[138:141], v[166:169], v[82:85]
	s_barrier
	v_mfma_f32_16x16x32_bf16 v[78:81], v[130:133], v[178:181], v[78:81]
	v_mfma_f32_16x16x32_bf16 v[90:93], v[138:141], v[178:181], v[90:93]
	v_mfma_f32_16x16x32_bf16 v[86:89], v[130:133], v[182:185], v[86:89]
	v_mfma_f32_16x16x32_bf16 v[102:105], v[138:141], v[182:185], v[102:105]
	v_mfma_f32_16x16x32_bf16 v[74:77], v[134:137], v[170:173], v[74:77]
	v_mfma_f32_16x16x32_bf16 v[70:73], v[142:145], v[170:173], v[70:73]
	v_mfma_f32_16x16x32_bf16 v[66:69], v[134:137], v[174:177], v[66:69]
	v_mfma_f32_16x16x32_bf16 v[82:85], v[142:145], v[174:177], v[82:85]
	v_mfma_f32_16x16x32_bf16 v[78:81], v[134:137], v[186:189], v[78:81]
	v_mfma_f32_16x16x32_bf16 v[90:93], v[142:145], v[186:189], v[90:93]
	v_mfma_f32_16x16x32_bf16 v[86:89], v[134:137], v[190:193], v[86:89]
	v_mfma_f32_16x16x32_bf16 v[102:105], v[142:145], v[190:193], v[102:105]
	v_mfma_f32_16x16x32_bf16 v[98:101], v[146:149], v[162:165], v[98:101]
	v_mfma_f32_16x16x32_bf16 v[94:97], v[154:157], v[162:165], v[94:97]
	v_mfma_f32_16x16x32_bf16 v[106:109], v[146:149], v[166:169], v[106:109]
	v_mfma_f32_16x16x32_bf16 v[110:113], v[154:157], v[166:169], v[110:113]
	v_mfma_f32_16x16x32_bf16 v[114:117], v[146:149], v[178:181], v[114:117]
	v_mfma_f32_16x16x32_bf16 v[118:121], v[154:157], v[178:181], v[118:121]
	v_mfma_f32_16x16x32_bf16 v[122:125], v[146:149], v[182:185], v[122:125]
	v_mfma_f32_16x16x32_bf16 v[126:129], v[154:157], v[182:185], v[126:129]
	v_mfma_f32_16x16x32_bf16 v[98:101], v[150:153], v[170:173], v[98:101]
	v_mfma_f32_16x16x32_bf16 v[94:97], v[158:161], v[170:173], v[94:97]
	v_mfma_f32_16x16x32_bf16 v[106:109], v[150:153], v[174:177], v[106:109]
	v_mfma_f32_16x16x32_bf16 v[110:113], v[158:161], v[174:177], v[110:113]
	v_mfma_f32_16x16x32_bf16 v[114:117], v[150:153], v[186:189], v[114:117]
	v_mfma_f32_16x16x32_bf16 v[118:121], v[158:161], v[186:189], v[118:121]
	v_mfma_f32_16x16x32_bf16 v[122:125], v[150:153], v[190:193], v[122:125]
	v_mfma_f32_16x16x32_bf16 v[126:129], v[158:161], v[190:193], v[126:129]
	s_barrier
	s_setprio 0
	s_mov_b32 m0, s53
	s_add_i32 s33, s31, 0x80
	ds_read_b128 v[162:165], v247 offset:49152
	ds_read_b128 v[166:169], v247 offset:51200
	ds_read_b128 v[170:173], v248 offset:49152
	ds_read_b128 v[174:177], v248 offset:51200
	ds_read_b128 v[178:181], v247 offset:53248
	ds_read_b128 v[182:185], v247 offset:55296
	ds_read_b128 v[186:189], v248 offset:53248
	ds_read_b128 v[190:193], v248 offset:55296
	buffer_load_dwordx4 v231, s[8:11], s33 offen lds
	s_mov_b32 m0, s54
	s_add_i32 s31, s31, 0x100080
	buffer_load_dwordx4 v234, s[8:11], s33 offen lds
	s_mov_b32 m0, s57
	s_nop 0
	buffer_load_dwordx4 v231, s[8:11], s31 offen lds
	s_mov_b32 m0, s58
	s_nop 0
	buffer_load_dwordx4 v234, s[8:11], s31 offen lds
	s_mov_b32 m0, s55
	s_nop 0
	buffer_load_dwordx4 v230, s[8:11], s30 offen lds
	s_mov_b32 m0, s56
	s_nop 0
	buffer_load_dwordx4 v233, s[8:11], s30 offen lds
	s_waitcnt vmcnt(8)
	s_waitcnt lgkmcnt(0)
	s_setprio 1
	s_barrier
	v_mfma_f32_16x16x32_bf16 v[10:13], v[130:133], v[162:165], v[10:13]
	v_mfma_f32_16x16x32_bf16 v[4:7], v[138:141], v[162:165], v[6:9]
	v_mfma_f32_16x16x32_bf16 v[0:3], v[130:133], v[166:169], v[0:3]
	v_mfma_f32_16x16x32_bf16 v[18:21], v[138:141], v[166:169], v[18:21]
	v_mfma_f32_16x16x32_bf16 v[14:17], v[130:133], v[178:181], v[14:17]
	v_mfma_f32_16x16x32_bf16 v[26:29], v[138:141], v[178:181], v[26:29]
	v_mfma_f32_16x16x32_bf16 v[22:25], v[130:133], v[182:185], v[22:25]
	v_mfma_f32_16x16x32_bf16 v[38:41], v[138:141], v[182:185], v[38:41]
	v_mfma_f32_16x16x32_bf16 v[10:13], v[134:137], v[170:173], v[10:13]
	v_mfma_f32_16x16x32_bf16 v[6:9], v[142:145], v[170:173], v[4:7]
	v_mfma_f32_16x16x32_bf16 v[2:5], v[134:137], v[174:177], v[0:3]
	v_mfma_f32_16x16x32_bf16 v[18:21], v[142:145], v[174:177], v[18:21]
	v_mfma_f32_16x16x32_bf16 v[14:17], v[134:137], v[186:189], v[14:17]
	v_mfma_f32_16x16x32_bf16 v[26:29], v[142:145], v[186:189], v[26:29]
	v_mfma_f32_16x16x32_bf16 v[22:25], v[134:137], v[190:193], v[22:25]
	v_mfma_f32_16x16x32_bf16 v[38:41], v[142:145], v[190:193], v[38:41]
	v_mfma_f32_16x16x32_bf16 v[34:37], v[146:149], v[162:165], v[34:37]
	v_mfma_f32_16x16x32_bf16 v[30:33], v[154:157], v[162:165], v[30:33]
	v_mfma_f32_16x16x32_bf16 v[42:45], v[146:149], v[166:169], v[42:45]
	v_mfma_f32_16x16x32_bf16 v[46:49], v[154:157], v[166:169], v[46:49]
	v_mfma_f32_16x16x32_bf16 v[50:53], v[146:149], v[178:181], v[50:53]
	v_mfma_f32_16x16x32_bf16 v[54:57], v[154:157], v[178:181], v[54:57]
	v_mfma_f32_16x16x32_bf16 v[58:61], v[146:149], v[182:185], v[58:61]
	v_mfma_f32_16x16x32_bf16 v[62:65], v[154:157], v[182:185], v[62:65]
	v_mfma_f32_16x16x32_bf16 v[34:37], v[150:153], v[170:173], v[34:37]
	v_mfma_f32_16x16x32_bf16 v[30:33], v[158:161], v[170:173], v[30:33]
	v_mfma_f32_16x16x32_bf16 v[42:45], v[150:153], v[174:177], v[42:45]
	v_mfma_f32_16x16x32_bf16 v[46:49], v[158:161], v[174:177], v[46:49]
	v_mfma_f32_16x16x32_bf16 v[50:53], v[150:153], v[186:189], v[50:53]
	v_mfma_f32_16x16x32_bf16 v[54:57], v[158:161], v[186:189], v[54:57]
	v_mfma_f32_16x16x32_bf16 v[58:61], v[150:153], v[190:193], v[58:61]
	v_mfma_f32_16x16x32_bf16 v[62:65], v[158:161], v[190:193], v[62:65]
	s_barrier
	s_setprio 0
	s_add_i32 s4, s4, 2
	s_addk_i32 s5, 0x100
	s_cmp_gt_u32 s4, 61
	s_cbranch_scc0 .LBB0_1251
	s_and_b64 vcc, exec, s[18:19]
	s_cbranch_vccz .LBB0_1254
	s_barrier
